# combo24: combo23 + prenorm_rows software prefetch (next row's loads issued before the current row is reduced; unrolled by two with two data register sets, last row peeled)
# baseline (speedup 1.0000x reference)
; __device__ __forceinline__ int opaque_tid() { int t = threadIdx.x; asm volatile("" : "+v"(t)); return t; }
; __device__ __forceinline__ unsigned pk2(float lo, float hi) { const f32x2 v = {lo, hi}; return __builtin_bit_cast(unsigned, __builtin_convertvector(v, hwbf16x2)); }
; __device__ __forceinline__ void prenorm_rows(const float* __restrict__ xin, bf16_t* __restrict__ an, float* __restrict__ rss, const float* __restrict__ modl, int coff) {
;     const int tid = opaque_tid(), lane = tid & 63, gw = blockIdx.x * 8 + (tid >> 6), NGW = GRID * 8;
; #pragma unroll 4
;     for (int t = gw; t < T; t += NGW) {
;         const f32x4* xr = (const f32x4*)(xin + (size_t)t * DM) + lane; f32x4 v[4]; float ss = 0.f;
; #pragma unroll
;         for (int j = 0; j < 4; ++j) { v[j] = xr[64 * j]; ss += (v[j][0] * v[j][0] + v[j][1] * v[j][1]) + (v[j][2] * v[j][2] + v[j][3] * v[j][3]); }
;         ss = wave_sum(ss); if (lane == 0) rss[t] = ss;
;         const float* mb = modl + (size_t)(t >> 13) * NMOD;
; #pragma unroll
;         for (int j = 0; j < 4; ++j) { const int col = 256 * j + 4 * lane;
;             const f32x4 sc = *(const f32x4*)(mb + coff + col);
;             const f32x4 h = v[j] * (sc + 1.0f);
;             u32x2 w; w.x = pk2(h[0], h[1]); w.y = pk2(h[2], h[3]); *(u32x2*)(an + (size_t)t * DM + col) = w; }
;     }
.LBB0_114:
	s_or_b64 exec, exec, s[2:3]
	v_mov_b32_e32 v0, v190
	s_barrier
	v_readlane_b32 s2, v252, 6
	v_ashrrev_i32_e32 v1, 6, v0
	s_nop 0
	v_add_u32_e32 v16, s2, v1
	s_mov_b32 s2, 0x8000
	v_cmp_gt_i32_e32 vcc, s2, v16
	s_and_saveexec_b64 s[6:7], vcc
	s_cbranch_execz .LBB0_119
	v_and_b32_e32 v1, 63, v0
	v_mbcnt_hi_u32_b32 v0, -1, v42
	v_and_b32_e32 v2, 64, v0
	v_add_u32_e32 v2, 64, v2
	v_xor_b32_e32 v3, 1, v0
	v_cmp_lt_i32_e32 vcc, v3, v2
	v_ashrrev_i32_e32 v17, 31, v16
	v_mov_b64_e32 v[8:9], 0x1f000000
	v_cndmask_b32_e32 v3, v0, v3, vcc
	v_lshlrev_b32_e32 v32, 2, v3
	v_xor_b32_e32 v3, 2, v0
	v_cmp_lt_i32_e32 vcc, v3, v2
	v_lshl_add_u64 v[20:21], v[16:17], 2, v[8:9]
	v_lshlrev_b64 v[8:9], 12, v[16:17]
	v_cndmask_b32_e32 v3, v0, v3, vcc
	v_lshlrev_b32_e32 v33, 2, v3
	v_xor_b32_e32 v3, 4, v0
	v_cmp_lt_i32_e32 vcc, v3, v2
	v_mov_b32_e32 v19, 0
	v_lshlrev_b64 v[22:23], 11, v[16:17]
	v_cndmask_b32_e32 v3, v0, v3, vcc
	v_lshlrev_b32_e32 v34, 2, v3
	v_xor_b32_e32 v3, 8, v0
	v_cmp_lt_i32_e32 vcc, v3, v2
	v_lshl_or_b32 v8, v1, 4, v8
	v_lshl_or_b32 v22, v1, 3, v22
	v_cndmask_b32_e32 v3, v0, v3, vcc
	v_lshlrev_b32_e32 v35, 2, v3
	v_xor_b32_e32 v3, 16, v0
	v_cmp_lt_i32_e32 vcc, v3, v2
	v_lshl_add_u64 v[24:25], s[68:69], 0, v[8:9]
	s_mov_b64 s[8:9], 0
	v_cndmask_b32_e32 v3, v0, v3, vcc
	v_lshlrev_b32_e32 v36, 2, v3
	v_xor_b32_e32 v3, 32, v0
	v_cmp_lt_i32_e32 vcc, v3, v2
	s_mov_b64 s[12:13], 0x1000
	s_mov_b32 s20, 0x3700000
	v_cndmask_b32_e32 v0, v0, v3, vcc
	v_lshlrev_b32_e32 v37, 2, v0
	v_lshlrev_b32_e32 v0, 2, v1
	v_or_b32_e32 v2, 0x100, v0
	v_or_b32_e32 v4, 0x200, v0
	v_or_b32_e32 v6, 0x300, v0
	v_cmp_eq_u32_e32 vcc, 0, v1
	v_lshlrev_b32_e32 v26, 2, v0
	v_lshlrev_b32_e32 v28, 2, v2
	v_lshlrev_b32_e32 v18, 2, v4
	v_lshlrev_b32_e32 v30, 2, v6
	s_mov_b64 s[14:15], 0x2000
	s_mov_b64 s[16:17], 0x400000
	s_mov_b64 s[18:19], 0x800000
	s_movk_i32 s21, 0x77ff
	v_mov_b32_e32 v27, v19
	v_mov_b32_e32 v29, v19
	s_branch .LBB0_117
.LBB0_117:
	global_load_dwordx4 v[0:3], v[24:25], off
	global_load_dwordx4 v[4:7], v[24:25], off offset:1024
	global_load_dwordx4 v[8:11], v[24:25], off offset:2048
	global_load_dwordx4 v[12:15], v[24:25], off offset:3072
.Lpn_loop:
	v_ashrrev_i32_e32 v76, 13, v16
	v_mul_i32_i24_e32 v78, 0x1800, v76
	v_ashrrev_i32_e32 v79, 31, v78
	v_lshl_add_u64 v[78:79], v[78:79], 2, s[76:77]
	v_lshl_add_u64 v[80:81], v[78:79], 0, s[12:13]
	v_lshl_add_u64 v[82:83], v[80:81], 0, v[26:27]
	global_load_dwordx4 v[60:63], v[82:83], off
	v_lshl_add_u64 v[82:83], v[80:81], 0, v[28:29]
	global_load_dwordx4 v[64:67], v[82:83], off
	v_lshl_add_u64 v[82:83], v[80:81], 0, v[18:19]
	global_load_dwordx4 v[68:71], v[82:83], off
	v_mov_b32_e32 v84, v30
	v_mov_b32_e32 v85, v19
	v_lshl_add_u64 v[82:83], v[80:81], 0, v[84:85]
	global_load_dwordx4 v[72:75], v[82:83], off
	v_lshl_add_u64 v[82:83], v[24:25], 0, s[18:19]
	global_load_dwordx4 v[88:91], v[82:83], off
	global_load_dwordx4 v[92:95], v[82:83], off offset:1024
	global_load_dwordx4 v[96:99], v[82:83], off offset:2048
	global_load_dwordx4 v[100:103], v[82:83], off offset:3072
	s_waitcnt vmcnt(11)
	v_mul_f32_e32 v17, v1, v1
	v_mul_f32_e32 v31, v3, v3
	s_waitcnt vmcnt(10)
	v_mul_f32_e32 v38, v5, v5
	v_mul_f32_e32 v39, v7, v7
	s_waitcnt vmcnt(9)
	v_mul_f32_e32 v40, v9, v9
	v_mul_f32_e32 v41, v11, v11
	v_fmac_f32_e32 v17, v0, v0
	v_fmac_f32_e32 v31, v2, v2
	v_fmac_f32_e32 v38, v4, v4
	v_fmac_f32_e32 v39, v6, v6
	s_waitcnt vmcnt(8)
	v_mul_f32_e32 v43, v13, v13
	v_mul_f32_e32 v44, v15, v15
	v_fmac_f32_e32 v40, v8, v8
	v_fmac_f32_e32 v41, v10, v10
	v_add_f32_e32 v17, v17, v31
	v_add_f32_e32 v31, v38, v39
	v_fmac_f32_e32 v43, v12, v12
	v_fmac_f32_e32 v44, v14, v14
	v_add_f32_e32 v38, v40, v41
	v_add_f32_e32 v17, v17, v31
	v_add_f32_e32 v17, v17, v38
	v_add_f32_e32 v31, v43, v44
	v_add_f32_e32 v17, v17, v31
	s_nop 1
	v_add_f32_dpp v17, v17, v17 quad_perm:[1,0,3,2] row_mask:0xf bank_mask:0xf
	s_nop 1
	v_add_f32_dpp v17, v17, v17 quad_perm:[2,3,0,1] row_mask:0xf bank_mask:0xf
	s_nop 1
	v_add_f32_dpp v17, v17, v17 row_half_mirror row_mask:0xf bank_mask:0xf
	s_nop 1
	v_add_f32_dpp v17, v17, v17 row_mirror row_mask:0xf bank_mask:0xf
	s_waitcnt lgkmcnt(0)
	ds_bpermute_b32 v31, v36, v17
	s_waitcnt lgkmcnt(0)
	v_add_f32_e32 v17, v17, v31
	ds_bpermute_b32 v31, v37, v17
	s_waitcnt lgkmcnt(0)
	v_add_f32_e32 v77, v17, v31
	v_lshl_add_u64 v[86:87], s[90:91], 0, v[20:21]
	v_lshl_add_u64 v[56:57], s[90:91], 0, v[22:23]
	v_add_u32_e32 v31, 0x800, v16
	v_cmp_lt_i32_e64 s[2:3], s21, v16
	v_add_co_u32_e64 v16, s[4:5], s20, v56
	v_lshl_add_u64 v[20:21], v[20:21], 0, s[14:15]
	s_nop 0
	v_addc_co_u32_e64 v17, s[4:5], 0, v57, s[4:5]
	v_lshl_add_u64 v[22:23], v[22:23], 0, s[16:17]
	v_lshl_add_u64 v[24:25], v[24:25], 0, s[18:19]
	s_or_b64 s[8:9], s[2:3], s[8:9]
	s_waitcnt vmcnt(7)
	v_pk_add_f32 v[62:63], v[62:63], 1.0 op_sel_hi:[1,0]
	v_pk_add_f32 v[60:61], v[60:61], 1.0 op_sel_hi:[1,0]
	s_waitcnt vmcnt(6)
	v_pk_add_f32 v[66:67], v[66:67], 1.0 op_sel_hi:[1,0]
	v_pk_add_f32 v[64:65], v[64:65], 1.0 op_sel_hi:[1,0]
	s_waitcnt vmcnt(5)
	v_pk_add_f32 v[70:71], v[70:71], 1.0 op_sel_hi:[1,0]
	v_pk_add_f32 v[68:69], v[68:69], 1.0 op_sel_hi:[1,0]
	s_waitcnt vmcnt(4)
	v_pk_add_f32 v[74:75], v[74:75], 1.0 op_sel_hi:[1,0]
	v_pk_add_f32 v[72:73], v[72:73], 1.0 op_sel_hi:[1,0]
	v_pk_mul_f32 v[2:3], v[2:3], v[62:63]
	v_pk_mul_f32 v[0:1], v[0:1], v[60:61]
	v_pk_mul_f32 v[6:7], v[6:7], v[66:67]
	v_pk_mul_f32 v[4:5], v[4:5], v[64:65]
	v_pk_mul_f32 v[10:11], v[10:11], v[70:71]
	v_pk_mul_f32 v[8:9], v[8:9], v[68:69]
	v_pk_mul_f32 v[14:15], v[14:15], v[74:75]
	v_pk_mul_f32 v[12:13], v[12:13], v[72:73]
	v_cvt_pk_bf16_f32 v0, v0, v1
	v_cvt_pk_bf16_f32 v1, v2, v3
	v_cvt_pk_bf16_f32 v2, v4, v5
	v_cvt_pk_bf16_f32 v3, v6, v7
	v_cvt_pk_bf16_f32 v4, v8, v9
	v_cvt_pk_bf16_f32 v5, v10, v11
	v_cvt_pk_bf16_f32 v6, v12, v13
	v_cvt_pk_bf16_f32 v7, v14, v15
	global_store_dwordx2 v[16:17], v[0:1], off
	global_store_dwordx2 v[16:17], v[2:3], off offset:512
	global_store_dwordx2 v[16:17], v[4:5], off offset:1024
	global_store_dwordx2 v[16:17], v[6:7], off offset:1536
	s_mov_b64 s[4:5], exec
	s_and_b64 exec, exec, vcc
	global_store_dword v[86:87], v77, off
	s_mov_b64 exec, s[4:5]
	v_mov_b32_e32 v16, v31
	s_andn2_b64 exec, exec, s[8:9]
	s_cbranch_execz .LBB0_119
; __device__ __forceinline__ unsigned pk2(float lo, float hi) { const f32x2 v = {lo, hi}; return __builtin_bit_cast(unsigned, __builtin_convertvector(v, hwbf16x2)); }
; __device__ __forceinline__ void prenorm_rows(const float* __restrict__ xin, bf16_t* __restrict__ an, float* __restrict__ rss, const float* __restrict__ modl, int coff) {
;     ...
;     for (int t = gw; t < T; t += NGW) {
;         const f32x4* xr = (const f32x4*)(xin + (size_t)t * DM) + lane; f32x4 v[4]; float ss = 0.f;
; #pragma unroll
;         for (int j = 0; j < 4; ++j) { v[j] = xr[64 * j]; ss += (v[j][0] * v[j][0] + v[j][1] * v[j][1]) + (v[j][2] * v[j][2] + v[j][3] * v[j][3]); }
;         ss = wave_sum(ss); if (lane == 0) rss[t] = ss;
;         const float* mb = modl + (size_t)(t >> 13) * NMOD;
; #pragma unroll
;         for (int j = 0; j < 4; ++j) { const int col = 256 * j + 4 * lane;
;             const f32x4 sc = *(const f32x4*)(mb + coff + col);
;             const f32x4 h = v[j] * (sc + 1.0f);
;             u32x2 w; w.x = pk2(h[0], h[1]); w.y = pk2(h[2], h[3]); *(u32x2*)(an + (size_t)t * DM + col) = w; }
;     }
	v_readfirstlane_b32 s24, v16
	s_cmp_gt_i32 s24, 0x77ff
	s_cbranch_scc1 .Lpn_last
	v_ashrrev_i32_e32 v76, 13, v16
	v_mul_i32_i24_e32 v78, 0x1800, v76
	v_ashrrev_i32_e32 v79, 31, v78
	v_lshl_add_u64 v[78:79], v[78:79], 2, s[76:77]
	v_lshl_add_u64 v[80:81], v[78:79], 0, s[12:13]
	v_lshl_add_u64 v[82:83], v[80:81], 0, v[26:27]
	global_load_dwordx4 v[60:63], v[82:83], off
	v_lshl_add_u64 v[82:83], v[80:81], 0, v[28:29]
	global_load_dwordx4 v[64:67], v[82:83], off
	v_lshl_add_u64 v[82:83], v[80:81], 0, v[18:19]
	global_load_dwordx4 v[68:71], v[82:83], off
	v_mov_b32_e32 v84, v30
	v_mov_b32_e32 v85, v19
	v_lshl_add_u64 v[82:83], v[80:81], 0, v[84:85]
	global_load_dwordx4 v[72:75], v[82:83], off
	v_lshl_add_u64 v[82:83], v[24:25], 0, s[18:19]
	global_load_dwordx4 v[0:3], v[82:83], off
	global_load_dwordx4 v[4:7], v[82:83], off offset:1024
	global_load_dwordx4 v[8:11], v[82:83], off offset:2048
	global_load_dwordx4 v[12:15], v[82:83], off offset:3072
	s_waitcnt vmcnt(11)
	v_mul_f32_e32 v17, v89, v89
	v_mul_f32_e32 v31, v91, v91
	s_waitcnt vmcnt(10)
	v_mul_f32_e32 v38, v93, v93
	v_mul_f32_e32 v39, v95, v95
	s_waitcnt vmcnt(9)
	v_mul_f32_e32 v40, v97, v97
	v_mul_f32_e32 v41, v99, v99
	v_fmac_f32_e32 v17, v88, v88
	v_fmac_f32_e32 v31, v90, v90
	v_fmac_f32_e32 v38, v92, v92
	v_fmac_f32_e32 v39, v94, v94
	s_waitcnt vmcnt(8)
	v_mul_f32_e32 v43, v101, v101
	v_mul_f32_e32 v44, v103, v103
	v_fmac_f32_e32 v40, v96, v96
	v_fmac_f32_e32 v41, v98, v98
	v_add_f32_e32 v17, v17, v31
	v_add_f32_e32 v31, v38, v39
	v_fmac_f32_e32 v43, v100, v100
	v_fmac_f32_e32 v44, v102, v102
	v_add_f32_e32 v38, v40, v41
	v_add_f32_e32 v17, v17, v31
	v_add_f32_e32 v17, v17, v38
	v_add_f32_e32 v31, v43, v44
	v_add_f32_e32 v17, v17, v31
	s_nop 1
	v_add_f32_dpp v17, v17, v17 quad_perm:[1,0,3,2] row_mask:0xf bank_mask:0xf
	s_nop 1
	v_add_f32_dpp v17, v17, v17 quad_perm:[2,3,0,1] row_mask:0xf bank_mask:0xf
	s_nop 1
	v_add_f32_dpp v17, v17, v17 row_half_mirror row_mask:0xf bank_mask:0xf
	s_nop 1
	v_add_f32_dpp v17, v17, v17 row_mirror row_mask:0xf bank_mask:0xf
	s_waitcnt lgkmcnt(0)
	ds_bpermute_b32 v31, v36, v17
	s_waitcnt lgkmcnt(0)
	v_add_f32_e32 v17, v17, v31
	ds_bpermute_b32 v31, v37, v17
	s_waitcnt lgkmcnt(0)
	v_add_f32_e32 v77, v17, v31
	v_lshl_add_u64 v[86:87], s[90:91], 0, v[20:21]
	v_lshl_add_u64 v[56:57], s[90:91], 0, v[22:23]
	v_add_u32_e32 v31, 0x800, v16
	v_cmp_lt_i32_e64 s[2:3], s21, v16
	v_add_co_u32_e64 v16, s[4:5], s20, v56
	v_lshl_add_u64 v[20:21], v[20:21], 0, s[14:15]
	s_nop 0
	v_addc_co_u32_e64 v17, s[4:5], 0, v57, s[4:5]
	v_lshl_add_u64 v[22:23], v[22:23], 0, s[16:17]
	v_lshl_add_u64 v[24:25], v[24:25], 0, s[18:19]
	s_or_b64 s[8:9], s[2:3], s[8:9]
	s_waitcnt vmcnt(7)
	v_pk_add_f32 v[62:63], v[62:63], 1.0 op_sel_hi:[1,0]
	v_pk_add_f32 v[60:61], v[60:61], 1.0 op_sel_hi:[1,0]
	s_waitcnt vmcnt(6)
	v_pk_add_f32 v[66:67], v[66:67], 1.0 op_sel_hi:[1,0]
	v_pk_add_f32 v[64:65], v[64:65], 1.0 op_sel_hi:[1,0]
	s_waitcnt vmcnt(5)
	v_pk_add_f32 v[70:71], v[70:71], 1.0 op_sel_hi:[1,0]
	v_pk_add_f32 v[68:69], v[68:69], 1.0 op_sel_hi:[1,0]
	s_waitcnt vmcnt(4)
	v_pk_add_f32 v[74:75], v[74:75], 1.0 op_sel_hi:[1,0]
	v_pk_add_f32 v[72:73], v[72:73], 1.0 op_sel_hi:[1,0]
	v_pk_mul_f32 v[90:91], v[90:91], v[62:63]
	v_pk_mul_f32 v[88:89], v[88:89], v[60:61]
	v_pk_mul_f32 v[94:95], v[94:95], v[66:67]
	v_pk_mul_f32 v[92:93], v[92:93], v[64:65]
	v_pk_mul_f32 v[98:99], v[98:99], v[70:71]
	v_pk_mul_f32 v[96:97], v[96:97], v[68:69]
	v_pk_mul_f32 v[102:103], v[102:103], v[74:75]
	v_pk_mul_f32 v[100:101], v[100:101], v[72:73]
	v_cvt_pk_bf16_f32 v88, v88, v89
	v_cvt_pk_bf16_f32 v89, v90, v91
	v_cvt_pk_bf16_f32 v90, v92, v93
	v_cvt_pk_bf16_f32 v91, v94, v95
	v_cvt_pk_bf16_f32 v92, v96, v97
	v_cvt_pk_bf16_f32 v93, v98, v99
	v_cvt_pk_bf16_f32 v94, v100, v101
	v_cvt_pk_bf16_f32 v95, v102, v103
	global_store_dwordx2 v[16:17], v[88:89], off
	global_store_dwordx2 v[16:17], v[90:91], off offset:512
	global_store_dwordx2 v[16:17], v[92:93], off offset:1024
	global_store_dwordx2 v[16:17], v[94:95], off offset:1536
	s_mov_b64 s[4:5], exec
	s_and_b64 exec, exec, vcc
	global_store_dword v[86:87], v77, off
	s_mov_b64 exec, s[4:5]
	v_mov_b32_e32 v16, v31
	s_andn2_b64 exec, exec, s[8:9]
	s_cbranch_execz .LBB0_119
	s_branch .Lpn_loop
; __device__ __forceinline__ unsigned pk2(float lo, float hi) { const f32x2 v = {lo, hi}; return __builtin_bit_cast(unsigned, __builtin_convertvector(v, hwbf16x2)); }
; __device__ __forceinline__ void prenorm_rows(const float* __restrict__ xin, bf16_t* __restrict__ an, float* __restrict__ rss, const float* __restrict__ modl, int coff) {
;     ...
;     for (int t = gw; t < T; t += NGW) {
;         const f32x4* xr = (const f32x4*)(xin + (size_t)t * DM) + lane; f32x4 v[4]; float ss = 0.f;
; #pragma unroll
;         for (int j = 0; j < 4; ++j) { v[j] = xr[64 * j]; ss += (v[j][0] * v[j][0] + v[j][1] * v[j][1]) + (v[j][2] * v[j][2] + v[j][3] * v[j][3]); }
;         ss = wave_sum(ss); if (lane == 0) rss[t] = ss;
;         const float* mb = modl + (size_t)(t >> 13) * NMOD;
; #pragma unroll
;         for (int j = 0; j < 4; ++j) { const int col = 256 * j + 4 * lane;
;             const f32x4 sc = *(const f32x4*)(mb + coff + col);
;             const f32x4 h = v[j] * (sc + 1.0f);
;             u32x2 w; w.x = pk2(h[0], h[1]); w.y = pk2(h[2], h[3]); *(u32x2*)(an + (size_t)t * DM + col) = w; }
;     }
.Lpn_last:
	v_ashrrev_i32_e32 v76, 13, v16
	v_mul_i32_i24_e32 v78, 0x1800, v76
	v_ashrrev_i32_e32 v79, 31, v78
	v_lshl_add_u64 v[78:79], v[78:79], 2, s[76:77]
	v_lshl_add_u64 v[80:81], v[78:79], 0, s[12:13]
	v_lshl_add_u64 v[82:83], v[80:81], 0, v[26:27]
	global_load_dwordx4 v[60:63], v[82:83], off
	v_lshl_add_u64 v[82:83], v[80:81], 0, v[28:29]
	global_load_dwordx4 v[64:67], v[82:83], off
	v_lshl_add_u64 v[82:83], v[80:81], 0, v[18:19]
	global_load_dwordx4 v[68:71], v[82:83], off
	v_mov_b32_e32 v84, v30
	v_mov_b32_e32 v85, v19
	v_lshl_add_u64 v[82:83], v[80:81], 0, v[84:85]
	global_load_dwordx4 v[72:75], v[82:83], off
	s_waitcnt vmcnt(7)
	v_mul_f32_e32 v17, v89, v89
	v_mul_f32_e32 v31, v91, v91
	s_waitcnt vmcnt(6)
	v_mul_f32_e32 v38, v93, v93
	v_mul_f32_e32 v39, v95, v95
	s_waitcnt vmcnt(5)
	v_mul_f32_e32 v40, v97, v97
	v_mul_f32_e32 v41, v99, v99
	v_fmac_f32_e32 v17, v88, v88
	v_fmac_f32_e32 v31, v90, v90
	v_fmac_f32_e32 v38, v92, v92
	v_fmac_f32_e32 v39, v94, v94
	s_waitcnt vmcnt(4)
	v_mul_f32_e32 v43, v101, v101
	v_mul_f32_e32 v44, v103, v103
	v_fmac_f32_e32 v40, v96, v96
	v_fmac_f32_e32 v41, v98, v98
	v_add_f32_e32 v17, v17, v31
	v_add_f32_e32 v31, v38, v39
	v_fmac_f32_e32 v43, v100, v100
	v_fmac_f32_e32 v44, v102, v102
	v_add_f32_e32 v38, v40, v41
	v_add_f32_e32 v17, v17, v31
	v_add_f32_e32 v17, v17, v38
	v_add_f32_e32 v31, v43, v44
	v_add_f32_e32 v17, v17, v31
	s_nop 1
	v_add_f32_dpp v17, v17, v17 quad_perm:[1,0,3,2] row_mask:0xf bank_mask:0xf
	s_nop 1
	v_add_f32_dpp v17, v17, v17 quad_perm:[2,3,0,1] row_mask:0xf bank_mask:0xf
	s_nop 1
	v_add_f32_dpp v17, v17, v17 row_half_mirror row_mask:0xf bank_mask:0xf
	s_nop 1
	v_add_f32_dpp v17, v17, v17 row_mirror row_mask:0xf bank_mask:0xf
	s_waitcnt lgkmcnt(0)
	ds_bpermute_b32 v31, v36, v17
	s_waitcnt lgkmcnt(0)
	v_add_f32_e32 v17, v17, v31
	ds_bpermute_b32 v31, v37, v17
	s_waitcnt lgkmcnt(0)
	v_add_f32_e32 v77, v17, v31
	v_lshl_add_u64 v[86:87], s[90:91], 0, v[20:21]
	v_lshl_add_u64 v[56:57], s[90:91], 0, v[22:23]
	v_add_u32_e32 v31, 0x800, v16
	v_cmp_lt_i32_e64 s[2:3], s21, v16
	v_add_co_u32_e64 v16, s[4:5], s20, v56
	v_lshl_add_u64 v[20:21], v[20:21], 0, s[14:15]
	s_nop 0
	v_addc_co_u32_e64 v17, s[4:5], 0, v57, s[4:5]
	v_lshl_add_u64 v[22:23], v[22:23], 0, s[16:17]
	v_lshl_add_u64 v[24:25], v[24:25], 0, s[18:19]
	s_or_b64 s[8:9], s[2:3], s[8:9]
	s_waitcnt vmcnt(3)
	v_pk_add_f32 v[62:63], v[62:63], 1.0 op_sel_hi:[1,0]
	v_pk_add_f32 v[60:61], v[60:61], 1.0 op_sel_hi:[1,0]
	s_waitcnt vmcnt(2)
	v_pk_add_f32 v[66:67], v[66:67], 1.0 op_sel_hi:[1,0]
	v_pk_add_f32 v[64:65], v[64:65], 1.0 op_sel_hi:[1,0]
	s_waitcnt vmcnt(1)
	v_pk_add_f32 v[70:71], v[70:71], 1.0 op_sel_hi:[1,0]
	v_pk_add_f32 v[68:69], v[68:69], 1.0 op_sel_hi:[1,0]
	s_waitcnt vmcnt(0)
	v_pk_add_f32 v[74:75], v[74:75], 1.0 op_sel_hi:[1,0]
	v_pk_add_f32 v[72:73], v[72:73], 1.0 op_sel_hi:[1,0]
	v_pk_mul_f32 v[90:91], v[90:91], v[62:63]
	v_pk_mul_f32 v[88:89], v[88:89], v[60:61]
	v_pk_mul_f32 v[94:95], v[94:95], v[66:67]
	v_pk_mul_f32 v[92:93], v[92:93], v[64:65]
	v_pk_mul_f32 v[98:99], v[98:99], v[70:71]
	v_pk_mul_f32 v[96:97], v[96:97], v[68:69]
	v_pk_mul_f32 v[102:103], v[102:103], v[74:75]
	v_pk_mul_f32 v[100:101], v[100:101], v[72:73]
	v_cvt_pk_bf16_f32 v88, v88, v89
	v_cvt_pk_bf16_f32 v89, v90, v91
	v_cvt_pk_bf16_f32 v90, v92, v93
	v_cvt_pk_bf16_f32 v91, v94, v95
	v_cvt_pk_bf16_f32 v92, v96, v97
	v_cvt_pk_bf16_f32 v93, v98, v99
	v_cvt_pk_bf16_f32 v94, v100, v101
	v_cvt_pk_bf16_f32 v95, v102, v103
	global_store_dwordx2 v[16:17], v[88:89], off
	global_store_dwordx2 v[16:17], v[90:91], off offset:512
	global_store_dwordx2 v[16:17], v[92:93], off offset:1024
	global_store_dwordx2 v[16:17], v[94:95], off offset:1536
	s_mov_b64 s[4:5], exec
	s_and_b64 exec, exec, vcc
	global_store_dword v[86:87], v77, off
	s_mov_b64 exec, s[4:5]
	v_mov_b32_e32 v16, v31
	s_andn2_b64 exec, exec, s[8:9]
	s_cbranch_execz .LBB0_119
	s_branch .LBB0_119
